# adaLN pass 2 token loop gets the same next-token activation prefetch
# baseline (speedup 1.0000x reference)
.LBB0_1377:
	s_or_b64 exec, exec, s[12:13]
	s_mov_b64 s[14:15], s[60:61]
	v_mov_b32_e32 v0, v172
	s_waitcnt lgkmcnt(0)
	v_mov_b32_e32 v2, v172
	s_barrier
	s_mov_b32 s2, s94
	v_ashrrev_i32_e32 v2, 6, v2
	s_nop 0
	v_lshl_add_u32 v6, s2, 3, v2
	v_cmp_gt_i32_e32 vcc, s11, v6
	s_and_saveexec_b64 s[12:13], vcc
	s_cbranch_execz .LBB0_1384
	s_load_dwordx4 s[44:47], s[14:15], 0x128
	s_load_dwordx2 s[6:7], s[14:15], 0x30
	v_readlane_b32 s2, v255, 48
	v_lshlrev_b32_e32 v0, 2, v0
	v_readlane_b32 s3, v255, 49
	s_waitcnt lgkmcnt(0)
	s_add_u32 s14, s46, 0x2a00000
	s_addc_u32 s15, s47, 0
	s_add_u32 s2, s46, s2
	v_and_b32_e32 v2, 0xfc, v0
	s_addc_u32 s3, s47, s3
	v_xor_b32_e32 v0, 32, v181
	s_add_u32 s16, s2, 0x5606000
	v_cmp_lt_i32_e32 vcc, v0, v182
	s_addc_u32 s17, s3, 0
	v_readlane_b32 s2, v255, 46
	v_cndmask_b32_e32 v0, v181, v0, vcc
	v_cmp_lt_i32_e32 vcc, v183, v182
	v_readlane_b32 s3, v255, 47
	v_lshlrev_b32_e32 v30, 2, v0
	v_cndmask_b32_e32 v0, v181, v183, vcc
	v_cmp_lt_i32_e32 vcc, v189, v182
	s_lshl_b64 s[18:19], s[2:3], 2
	v_lshlrev_b32_e32 v31, 2, v0
	v_cndmask_b32_e32 v0, v181, v189, vcc
	v_cmp_lt_i32_e32 vcc, v190, v182
	s_add_u32 s2, s6, s18
	v_lshlrev_b32_e32 v32, 2, v0
	v_cndmask_b32_e32 v0, v181, v190, vcc
	v_cmp_lt_i32_e32 vcc, v191, v182
	s_addc_u32 s3, s7, s19
	v_lshlrev_b32_e32 v33, 2, v0
	v_cndmask_b32_e32 v0, v181, v191, vcc
	v_cmp_lt_i32_e32 vcc, v188, v182
	s_add_u32 s6, s2, 0x2000
	v_lshlrev_b32_e32 v34, 2, v0
	v_cndmask_b32_e32 v0, v181, v188, vcc
	s_addc_u32 s7, s3, 0
	v_lshlrev_b32_e32 v35, 2, v0
	v_lshlrev_b32_e32 v0, 2, v2
	v_or_b32_e32 v4, 0x100, v2
	v_lshl_add_u64 v[8:9], s[6:7], 0, v[0:1]
	v_lshlrev_b32_e32 v0, 2, v4
	v_or_b32_e32 v20, 0x200, v2
	v_lshl_add_u64 v[10:11], s[6:7], 0, v[0:1]
	v_lshlrev_b32_e32 v0, 2, v20
	v_or_b32_e32 v22, 0x300, v2
	v_lshl_add_u64 v[12:13], s[6:7], 0, v[0:1]
	v_lshlrev_b32_e32 v0, 2, v22
	v_lshl_add_u64 v[14:15], s[6:7], 0, v[0:1]
	v_lshlrev_b32_e32 v0, 1, v2
	v_lshl_add_u64 v[16:17], s[46:47], 0, v[0:1]
	s_mov_b64 s[2:3], 0x3200000
	v_lshl_add_u64 v[16:17], v[16:17], 0, s[2:3]
	s_mov_b64 s[18:19], 0
	v_lshlrev_b32_e32 v0, 2, v2
	v_lshlrev_b32_e32 v18, 2, v4
	v_lshlrev_b32_e32 v20, 2, v20
	v_lshlrev_b32_e32 v22, 2, v22
	v_mov_b32_e32 v132, v6
	v_cmp_lt_i32_e32 vcc, s97, v132
	v_add_u32_e32 v133, 0xffffc000, v132
	v_mov_b32_e32 v134, s14
	v_mov_b32_e32 v135, s15
	v_mov_b32_e32 v136, s44
	v_mov_b32_e32 v137, s45
	v_cndmask_b32_e32 v132, v132, v133, vcc
	v_cndmask_b32_e32 v134, v136, v134, vcc
	v_cndmask_b32_e32 v135, v137, v135, vcc
	v_mov_b32_e32 v133, 0
	v_lshlrev_b64 v[132:133], 12, v[132:133]
	v_lshl_add_u64 v[132:133], v[134:135], 0, v[132:133]
	v_lshl_add_u64 v[132:133], v[132:133], 0, v[0:1]
	global_load_dwordx4 v[114:117], v[132:133], off
	global_load_dwordx4 v[118:121], v[132:133], off offset:1024
	global_load_dwordx4 v[122:125], v[132:133], off offset:2048
	global_load_dwordx4 v[126:129], v[132:133], off offset:3072
	s_waitcnt vmcnt(0)
	s_branch .LBB0_1380
.LBB0_1379:
	s_or_b64 exec, exec, s[46:47]
	s_waitcnt vmcnt(4)
	v_mov_b32_e32 v36, v114
	v_mov_b32_e32 v37, v115
	v_mov_b32_e32 v38, v116
	v_mov_b32_e32 v39, v117
	v_mov_b32_e32 v40, v118
	v_mov_b32_e32 v41, v119
	v_mov_b32_e32 v42, v120
	v_mov_b32_e32 v43, v121
	v_mov_b32_e32 v44, v122
	v_mov_b32_e32 v45, v123
	v_mov_b32_e32 v46, v124
	v_mov_b32_e32 v47, v125
	v_mov_b32_e32 v2, v126
	v_mov_b32_e32 v3, v127
	v_mov_b32_e32 v4, v128
	v_mov_b32_e32 v5, v129
	s_nop 0
	s_nop 0
	global_load_dwordx4 v[48:51], v[8:9], off
	global_load_dwordx4 v[78:81], v[10:11], off
	global_load_dwordx4 v[90:93], v[12:13], off
	global_load_dwordx4 v[102:105], v[14:15], off
	v_min_i32_e32 v19, 0x4000, v6
	v_ashrrev_i32_e32 v19, 11, v19
	v_mul_hi_i32_i24_e32 v25, 0x9000, v19
	v_mul_i32_i24_e32 v24, 0x9000, v19
	v_lshl_add_u64 v[24:25], s[16:17], 0, v[24:25]
	v_lshl_add_u64 v[26:27], v[24:25], 0, s[38:39]
	v_lshl_add_u64 v[28:29], v[26:27], 0, v[0:1]
	global_load_dwordx4 v[52:55], v[28:29], off
	global_load_dwordx4 v[82:85], v[28:29], off offset:1024
	global_load_dwordx4 v[94:97], v[28:29], off offset:2048
	global_load_dwordx4 v[106:109], v[28:29], off offset:3072
	v_lshl_add_u64 v[28:29], v[24:25], 0, v[0:1]
	global_load_dwordx4 v[56:59], v[28:29], off
	global_load_dwordx4 v[86:89], v[28:29], off offset:1024
	global_load_dwordx4 v[98:101], v[28:29], off offset:2048
	global_load_dwordx4 v[110:113], v[28:29], off offset:3072
	v_lshl_add_u32 v132, s42, 3, v6
	v_mov_b32_e32 v134, s14
	v_cmp_gt_i32_e32 vcc, s11, v132
	v_mov_b32_e32 v135, s15
	v_mov_b32_e32 v136, s44
	v_cndmask_b32_e32 v132, v6, v132, vcc
	v_cmp_lt_i32_e32 vcc, s97, v132
	v_add_u32_e32 v133, 0xffffc000, v132
	v_mov_b32_e32 v134, s14
	v_mov_b32_e32 v135, s15
	v_mov_b32_e32 v136, s44
	v_mov_b32_e32 v137, s45
	v_cndmask_b32_e32 v132, v132, v133, vcc
	v_cndmask_b32_e32 v134, v136, v134, vcc
	v_cndmask_b32_e32 v135, v137, v135, vcc
	v_mov_b32_e32 v133, 0
	v_lshlrev_b64 v[132:133], 12, v[132:133]
	v_lshl_add_u64 v[132:133], v[134:135], 0, v[132:133]
	v_lshl_add_u64 v[132:133], v[132:133], 0, v[0:1]
	global_load_dwordx4 v[114:117], v[132:133], off
	global_load_dwordx4 v[118:121], v[132:133], off offset:1024
	global_load_dwordx4 v[122:125], v[132:133], off offset:2048
	global_load_dwordx4 v[126:129], v[132:133], off offset:3072
	s_mov_b32 s2, s42
	v_mov_b32_e32 v60, v37
	v_mov_b32_e32 v61, v41
	v_mov_b32_e32 v24, v36
	v_mov_b32_e32 v25, v40
	v_mov_b32_e32 v68, v45
	v_mov_b32_e32 v69, v3
	v_pk_mul_f32 v[60:61], v[60:61], v[60:61]
	v_mov_b32_e32 v62, v38
	v_mov_b32_e32 v63, v42
	v_mov_b32_e32 v66, v44
	v_mov_b32_e32 v67, v2
	v_pk_mul_f32 v[68:69], v[68:69], v[68:69]
	v_pk_fma_f32 v[24:25], v[24:25], v[24:25], v[60:61]
	v_mov_b32_e32 v64, v39
	v_mov_b32_e32 v65, v43
	v_mov_b32_e32 v70, v46
	v_mov_b32_e32 v71, v4
	v_pk_fma_f32 v[60:61], v[66:67], v[66:67], v[68:69]
	v_pk_fma_f32 v[24:25], v[62:63], v[62:63], v[24:25]
	v_mov_b32_e32 v72, v47
	v_mov_b32_e32 v73, v5
	v_pk_fma_f32 v[60:61], v[70:71], v[70:71], v[60:61]
	v_pk_fma_f32 v[24:25], v[64:65], v[64:65], v[24:25]
	v_pk_fma_f32 v[60:61], v[72:73], v[72:73], v[60:61]
	v_add_f32_e32 v19, v24, v25
	v_add_f32_e32 v19, v19, v60
	v_add_f32_e32 v19, v19, v61
	ds_bpermute_b32 v21, v30, v19
	v_lshlrev_b64 v[24:25], 11, v[6:7]
	s_waitcnt vmcnt(15)
	v_mov_b32_e32 v60, v48
	v_mov_b32_e32 v48, v36
	v_mov_b32_e32 v36, v37
	s_waitcnt lgkmcnt(0)
	v_add_f32_e32 v19, v19, v21
	ds_bpermute_b32 v21, v31, v19
	v_mov_b32_e32 v37, v39
	s_waitcnt vmcnt(7)
	v_mov_b32_e32 v62, v56
	v_mov_b32_e32 v61, v50
	v_mov_b32_e32 v50, v49
	s_waitcnt lgkmcnt(0)
	v_add_f32_e32 v21, v19, v21
	v_mov_b32_e32 v49, v38
	v_mov_b32_e32 v39, v54
	v_mov_b32_e32 v54, v53
	v_mov_b32_e32 v38, v52
	s_waitcnt lgkmcnt(0)
	s_nop 1
	v_add_f32_dpp v7, v21, v21 row_ror:8 row_mask:0xf bank_mask:0xf bound_ctrl:1
	v_mov_b32_e32 v63, v58
	v_mov_b32_e32 v58, v57
	v_pk_add_f32 v[52:53], v[54:55], 1.0 op_sel_hi:[1,0]
	v_pk_add_f32 v[38:39], v[38:39], 1.0 op_sel_hi:[1,0]
	s_waitcnt lgkmcnt(0)
	s_nop 1
	v_add_f32_dpp v7, v7, v7 row_ror:4 row_mask:0xf bank_mask:0xf bound_ctrl:1
	v_lshl_add_u64 v[24:25], v[16:17], 0, v[24:25]
	v_mov_b32_e32 v19, v1
	s_waitcnt lgkmcnt(0)
	s_nop 1
	v_add_f32_dpp v7, v7, v7 quad_perm:[2,3,0,1] row_mask:0xf bank_mask:0xf bound_ctrl:1
	s_waitcnt lgkmcnt(0)
	s_nop 1
	v_add_f32_dpp v7, v7, v7 quad_perm:[1,0,3,2] row_mask:0xf bank_mask:0xf bound_ctrl:1
	v_fmamk_f32 v7, v7, 0x3a800000, v174
	v_mul_f32_e32 v21, 0x4b800000, v7
	v_cmp_gt_f32_e32 vcc, s27, v7
	s_nop 1
	v_cndmask_b32_e32 v7, v7, v21, vcc
	v_rsq_f32_e32 v7, v7
	s_nop 0
	v_mul_f32_e32 v21, 0x45800000, v7
	v_cndmask_b32_e32 v56, v7, v21, vcc
	v_pk_mul_f32 v[36:37], v[36:37], v[56:57] op_sel_hi:[1,0]
	v_pk_mul_f32 v[48:49], v[48:49], v[56:57] op_sel_hi:[1,0]
	v_pk_mul_f32 v[36:37], v[50:51], v[36:37]
	v_pk_mul_f32 v[48:49], v[60:61], v[48:49]
	v_pk_fma_f32 v[36:37], v[52:53], v[36:37], v[58:59]
	v_pk_fma_f32 v[38:39], v[38:39], v[48:49], v[62:63]
	v_cvt_pk_bf16_f32 v21, v38, v36
	v_cvt_pk_bf16_f32 v37, v39, v37
	v_mov_b32_e32 v36, v21
	global_store_dwordx2 v[24:25], v[36:37], off
	v_lshl_add_u64 v[48:49], v[26:27], 0, v[18:19]
	s_waitcnt vmcnt(5)
	v_mov_b32_e32 v52, v86
	v_mov_b32_e32 v53, v87
	v_mov_b32_e32 v54, v88
	v_mov_b32_e32 v55, v89
	v_mov_b32_e32 v48, v82
	v_mov_b32_e32 v49, v83
	v_mov_b32_e32 v50, v84
	v_mov_b32_e32 v51, v85
	v_mov_b32_e32 v36, v78
	v_mov_b32_e32 v37, v79
	v_mov_b32_e32 v38, v80
	v_mov_b32_e32 v39, v81
	v_mov_b32_e32 v58, v40
	v_mov_b32_e32 v59, v42
	v_mov_b32_e32 v42, v41
	v_pk_mul_f32 v[40:41], v[58:59], v[56:57] op_sel_hi:[1,0]
	v_pk_mul_f32 v[42:43], v[42:43], v[56:57] op_sel_hi:[1,0]
	v_mov_b32_e32 v21, v1
	v_mov_b32_e32 v58, v36
	v_mov_b32_e32 v59, v38
	v_mov_b32_e32 v60, v48
	v_mov_b32_e32 v61, v50
	v_mov_b32_e32 v38, v37
	v_mov_b32_e32 v50, v49
	v_mov_b32_e32 v62, v52
	v_mov_b32_e32 v63, v54
	v_mov_b32_e32 v54, v53
	v_pk_mul_f32 v[36:37], v[40:41], v[58:59]
	v_pk_add_f32 v[40:41], v[60:61], 1.0 op_sel_hi:[1,0]
	v_pk_mul_f32 v[38:39], v[42:43], v[38:39]
	v_pk_add_f32 v[42:43], v[50:51], 1.0 op_sel_hi:[1,0]
	v_pk_fma_f32 v[36:37], v[36:37], v[40:41], v[62:63]
	v_pk_fma_f32 v[38:39], v[38:39], v[42:43], v[54:55]
	v_cvt_pk_bf16_f32 v19, v36, v38
	v_cvt_pk_bf16_f32 v37, v37, v39
	v_mov_b32_e32 v36, v19
	global_store_dwordx2 v[24:25], v[36:37], off offset:512
	v_lshl_add_u64 v[40:41], v[26:27], 0, v[20:21]
	v_mov_b32_e32 v48, v98
	v_mov_b32_e32 v49, v99
	v_mov_b32_e32 v50, v100
	v_mov_b32_e32 v51, v101
	v_mov_b32_e32 v40, v94
	v_mov_b32_e32 v41, v95
	v_mov_b32_e32 v42, v96
	v_mov_b32_e32 v43, v97
	v_mov_b32_e32 v36, v90
	v_mov_b32_e32 v37, v91
	v_mov_b32_e32 v38, v92
	v_mov_b32_e32 v39, v93
	v_mov_b32_e32 v52, v44
	v_mov_b32_e32 v53, v46
	v_mov_b32_e32 v44, v45
	v_mov_b32_e32 v45, v47
	v_pk_mul_f32 v[46:47], v[52:53], v[56:57] op_sel_hi:[1,0]
	v_pk_mul_f32 v[44:45], v[44:45], v[56:57] op_sel_hi:[1,0]
	v_mov_b32_e32 v23, v1
	v_lshl_add_u64 v[26:27], v[26:27], 0, v[22:23]
	v_mov_b32_e32 v52, v36
	v_mov_b32_e32 v53, v38
	v_mov_b32_e32 v54, v40
	v_mov_b32_e32 v55, v42
	v_mov_b32_e32 v38, v37
	v_mov_b32_e32 v42, v41
	v_mov_b32_e32 v58, v48
	v_mov_b32_e32 v59, v50
	v_mov_b32_e32 v50, v49
	v_pk_mul_f32 v[36:37], v[46:47], v[52:53]
	v_pk_add_f32 v[40:41], v[54:55], 1.0 op_sel_hi:[1,0]
	v_pk_mul_f32 v[38:39], v[44:45], v[38:39]
	v_pk_add_f32 v[42:43], v[42:43], 1.0 op_sel_hi:[1,0]
	v_pk_fma_f32 v[36:37], v[36:37], v[40:41], v[58:59]
	v_pk_fma_f32 v[38:39], v[38:39], v[42:43], v[50:51]
	v_cvt_pk_bf16_f32 v19, v36, v38
	v_cvt_pk_bf16_f32 v37, v37, v39
	v_mov_b32_e32 v36, v19
	global_store_dwordx2 v[24:25], v[36:37], off offset:1024
	v_mov_b32_e32 v26, v110
	v_mov_b32_e32 v27, v111
	v_mov_b32_e32 v28, v112
	v_mov_b32_e32 v29, v113
	v_mov_b32_e32 v40, v106
	v_mov_b32_e32 v41, v107
	v_mov_b32_e32 v42, v108
	v_mov_b32_e32 v43, v109
	v_mov_b32_e32 v36, v102
	v_mov_b32_e32 v37, v103
	v_mov_b32_e32 v38, v104
	v_mov_b32_e32 v39, v105
	v_mov_b32_e32 v44, v2
	v_mov_b32_e32 v45, v4
	v_mov_b32_e32 v4, v3
	v_pk_mul_f32 v[2:3], v[44:45], v[56:57] op_sel_hi:[1,0]
	v_pk_mul_f32 v[4:5], v[4:5], v[56:57] op_sel_hi:[1,0]
	v_mov_b32_e32 v47, v42
	v_mov_b32_e32 v45, v38
	v_mov_b32_e32 v38, v37
	v_mov_b32_e32 v42, v41
	v_mov_b32_e32 v44, v36
	v_mov_b32_e32 v46, v40
	v_mov_b32_e32 v49, v28
	v_mov_b32_e32 v28, v27
	v_pk_mul_f32 v[4:5], v[4:5], v[38:39]
	v_pk_add_f32 v[36:37], v[42:43], 1.0 op_sel_hi:[1,0]
	v_mov_b32_e32 v48, v26
	v_pk_mul_f32 v[2:3], v[2:3], v[44:45]
	v_pk_add_f32 v[26:27], v[46:47], 1.0 op_sel_hi:[1,0]
	v_pk_fma_f32 v[4:5], v[4:5], v[36:37], v[28:29]
	v_pk_fma_f32 v[2:3], v[2:3], v[26:27], v[48:49]
	v_cvt_pk_bf16_f32 v3, v3, v5
	v_and_b32_sdwa v23, v4, v177 dst_sel:DWORD dst_unused:UNUSED_PAD src0_sel:WORD_1 src1_sel:DWORD
	v_and_b32_sdwa v19, v2, v177 dst_sel:DWORD dst_unused:UNUSED_PAD src0_sel:WORD_1 src1_sel:DWORD
	v_add3_u32 v4, v4, v23, s28
	v_add3_u32 v2, v2, v19, s28
	v_and_b32_e32 v4, 0xffff0000, v4
	v_or_b32_sdwa v2, v4, v2 dst_sel:DWORD dst_unused:UNUSED_PAD src0_sel:DWORD src1_sel:WORD_1
	global_store_dwordx2 v[24:25], v[2:3], off offset:1536
	s_nop 0
	v_lshl_add_u32 v6, s2, 3, v6
	v_cmp_le_i32_e32 vcc, s11, v6
	s_or_b64 s[18:19], vcc, s[18:19]
	s_andn2_b64 exec, exec, s[18:19]
	s_cbranch_execz .LBB0_1384
